# attention epilogue: fifteen serialized sub-layer-norm gain loads issued together with the first one (into dead loop temporaries), one wait instead of sixteen
# speedup vs baseline: 1.0058x; 1.0028x over previous
; #define LAS __attribute__((address_space(3)))
; __device__ __forceinline__ unsigned cvt_pk_bf16(float lo, float hi) { unsigned r; asm volatile("v_cvt_pk_bf16_f32 %0, %1, %2" : "=v"(r) : "v"(lo), "v"(hi)); return r; }
; __device__ __forceinline__ float xhalf_sum(float v) { auto rr = __builtin_amdgcn_permlane32_swap(__float_as_uint(v), __float_as_uint(v), false, false); return __uint_as_float(rr[0]) + __uint_as_float(rr[1]); }
; __device__ __forceinline__ void attn_phase(const Args& A, LAS unsigned char* lds, int vcu, int G, const int tid) {
;     ...
;         if (c == 0) {
;             float ss = 0.f;
; #pragma unroll
;             for (int i = 0; i < 4; ++i)
; #pragma unroll
;                 for (int r = 0; r < 16; ++r) { const float d = o[i][r] * inv - scr[(i * 16 + r) * 64 + lane]; o[i][r] = d; ss += d * d; }
;             ss = xhalf_sum(ss);
;             const float rn = (1.0f - LAMBDA_INIT) / sqrtf(ss * (1.0f / 128.0f) + RMS_EPS);
;             int ln = lane; asm volatile("" : "+v"(ln));
;             const int er32 = ln & 31, ehi = ln >> 5;
;             LAS unsigned char* stg = lds + 65536 + qi * (32 * 272);
;             const float* sg = A.in[I_SUBG] + 4 * ehi;
; #pragma unroll
;             for (int i = 0; i < 4; ++i)
; #pragma unroll
;                 for (int rq = 0; rq < 4; ++rq) { const f32x4 gq = *(const f32x4*)(sg + 32 * i + 8 * rq);
;                     u32x2 w; w.x = cvt_pk_bf16(o[i][4 * rq] * rn * gq[0], o[i][4 * rq + 1] * rn * gq[1]); w.y = cvt_pk_bf16(o[i][4 * rq + 2] * rn * gq[2], o[i][4 * rq + 3] * rn * gq[3]);
;                     *(LAS u32x2*)(stg + er32 * 272 + (32 * i + 8 * rq + 4 * ehi) * 2) = w; }
.LBB0_963:
	s_and_b64 vcc, exec, s[4:5]
	s_waitcnt vmcnt(0) lgkmcnt(0)
	s_barrier
	s_cbranch_vccnz .LBB0_839
	ds_read2st64_b32 v[34:35], v210 offset1:1
	ds_read2st64_b32 v[36:37], v210 offset0:2 offset1:3
	ds_read2st64_b32 v[38:39], v210 offset0:4 offset1:5
	ds_read2st64_b32 v[40:41], v210 offset0:6 offset1:7
	s_ashr_i32 s39, s38, 31
	s_waitcnt lgkmcnt(3)
	v_fma_f32 v33, v80, v32, -v34
	v_fma_f32 v46, v81, v32, -v35
	ds_read2st64_b32 v[34:35], v210 offset0:8 offset1:9
	s_waitcnt lgkmcnt(3)
	v_fma_f32 v48, v82, v32, -v36
	v_fma_f32 v49, v83, v32, -v37
	s_waitcnt lgkmcnt(2)
	v_fma_f32 v50, v84, v32, -v38
	v_fma_f32 v51, v85, v32, -v39
	s_waitcnt lgkmcnt(1)
	v_fma_f32 v52, v86, v32, -v40
	v_fma_f32 v53, v87, v32, -v41
	ds_read2st64_b32 v[36:37], v210 offset0:10 offset1:11
	ds_read2st64_b32 v[38:39], v210 offset0:12 offset1:13
	ds_read2st64_b32 v[40:41], v210 offset0:14 offset1:15
	s_waitcnt lgkmcnt(3)
	v_fma_f32 v54, v88, v32, -v34
	v_fma_f32 v55, v89, v32, -v35
	ds_read2st64_b32 v[34:35], v210 offset0:16 offset1:17
	s_waitcnt lgkmcnt(3)
	v_fma_f32 v56, v90, v32, -v36
	v_fma_f32 v57, v91, v32, -v37
	s_waitcnt lgkmcnt(2)
	v_fma_f32 v58, v92, v32, -v38
	v_fma_f32 v59, v93, v32, -v39
	s_waitcnt lgkmcnt(1)
	v_fma_f32 v60, v94, v32, -v40
	v_fma_f32 v61, v95, v32, -v41
	ds_read2st64_b32 v[36:37], v210 offset0:18 offset1:19
	ds_read2st64_b32 v[38:39], v210 offset0:20 offset1:21
	ds_read2st64_b32 v[40:41], v210 offset0:22 offset1:23
	s_waitcnt lgkmcnt(3)
	v_fma_f32 v62, v64, v32, -v34
	v_fma_f32 v63, v65, v32, -v35
	ds_read2st64_b32 v[34:35], v210 offset0:24 offset1:25
	s_waitcnt lgkmcnt(3)
	v_fma_f32 v64, v66, v32, -v36
	v_fma_f32 v65, v67, v32, -v37
	s_waitcnt lgkmcnt(2)
	v_fma_f32 v66, v68, v32, -v38
	v_fma_f32 v67, v69, v32, -v39
	s_waitcnt lgkmcnt(1)
	v_fma_f32 v68, v70, v32, -v40
	v_fma_f32 v69, v71, v32, -v41
	ds_read2st64_b32 v[36:37], v210 offset0:26 offset1:27
	ds_read2st64_b32 v[38:39], v210 offset0:28 offset1:29
	ds_read2st64_b32 v[40:41], v210 offset0:30 offset1:31
	v_mul_f32_e32 v47, v46, v46
	v_fmac_f32_e32 v47, v33, v33
	v_fmac_f32_e32 v47, v48, v48
	v_fmac_f32_e32 v47, v49, v49
	s_waitcnt lgkmcnt(3)
	v_fma_f32 v70, v72, v32, -v34
	v_fma_f32 v71, v73, v32, -v35
	ds_read2st64_b32 v[34:35], v210 offset0:32 offset1:33
	v_fmac_f32_e32 v47, v50, v50
	s_waitcnt lgkmcnt(3)
	v_fma_f32 v72, v74, v32, -v36
	v_fma_f32 v73, v75, v32, -v37
	s_waitcnt lgkmcnt(2)
	v_fma_f32 v74, v76, v32, -v38
	v_fma_f32 v75, v77, v32, -v39
	s_waitcnt lgkmcnt(1)
	v_fma_f32 v76, v78, v32, -v40
	v_fma_f32 v77, v79, v32, -v41
	ds_read2st64_b32 v[36:37], v210 offset0:34 offset1:35
	ds_read2st64_b32 v[38:39], v210 offset0:36 offset1:37
	ds_read2st64_b32 v[40:41], v210 offset0:38 offset1:39
	v_fmac_f32_e32 v47, v51, v51
	v_fmac_f32_e32 v47, v52, v52
	v_fmac_f32_e32 v47, v53, v53
	v_fmac_f32_e32 v47, v54, v54
	s_waitcnt lgkmcnt(3)
	v_fma_f32 v78, v16, v32, -v34
	v_fma_f32 v79, v17, v32, -v35
	ds_read2st64_b32 v[16:17], v210 offset0:40 offset1:41
	v_fmac_f32_e32 v47, v55, v55
	s_waitcnt lgkmcnt(3)
	v_fma_f32 v80, v18, v32, -v36
	v_fma_f32 v81, v19, v32, -v37
	s_waitcnt lgkmcnt(2)
	v_fma_f32 v82, v20, v32, -v38
	v_fma_f32 v83, v21, v32, -v39
	s_waitcnt lgkmcnt(1)
	v_fma_f32 v84, v22, v32, -v40
	v_fma_f32 v85, v23, v32, -v41
	ds_read2st64_b32 v[18:19], v210 offset0:42 offset1:43
	ds_read2st64_b32 v[20:21], v210 offset0:44 offset1:45
	ds_read2st64_b32 v[22:23], v210 offset0:46 offset1:47
	v_fmac_f32_e32 v47, v56, v56
	v_fmac_f32_e32 v47, v57, v57
	v_fmac_f32_e32 v47, v58, v58
	v_mov_b32_e32 v92, v201
	v_fmac_f32_e32 v47, v59, v59
	s_waitcnt lgkmcnt(3)
	v_fma_f32 v86, v24, v32, -v16
	v_fma_f32 v87, v25, v32, -v17
	s_waitcnt lgkmcnt(2)
	v_fma_f32 v88, v26, v32, -v18
	v_fma_f32 v89, v27, v32, -v19
	s_waitcnt lgkmcnt(1)
	v_fma_f32 v90, v28, v32, -v20
	v_fma_f32 v91, v29, v32, -v21
	ds_read2st64_b32 v[24:25], v210 offset0:48 offset1:49
	ds_read2st64_b32 v[26:27], v210 offset0:50 offset1:51
	ds_read2st64_b32 v[28:29], v210 offset0:52 offset1:53
	ds_read2st64_b32 v[34:35], v210 offset0:54 offset1:55
	ds_read2st64_b32 v[36:37], v210 offset0:56 offset1:57
	ds_read2st64_b32 v[38:39], v210 offset0:58 offset1:59
	ds_read2st64_b32 v[40:41], v210 offset0:60 offset1:61
	ds_read2st64_b32 v[42:43], v210 offset0:62 offset1:63
	v_fmac_f32_e32 v47, v60, v60
	v_ashrrev_i32_e32 v16, 3, v92
	v_and_b32_e32 v44, -4, v16
	v_fmac_f32_e32 v47, v61, v61
	v_ashrrev_i32_e32 v45, 31, v44
	v_fmac_f32_e32 v47, v62, v62
	v_lshl_add_u64 v[16:17], v[44:45], 2, s[76:77]
	v_fmac_f32_e32 v47, v63, v63
	global_load_dwordx4 v[18:21], v[16:17], off
	global_load_dwordx4 v[96:99], v[16:17], off offset:32
	global_load_dwordx4 v[100:103], v[16:17], off offset:64
	global_load_dwordx4 v[104:107], v[16:17], off offset:96
	global_load_dwordx4 v[108:111], v[16:17], off offset:128
	global_load_dwordx4 v[112:115], v[16:17], off offset:160
	global_load_dwordx4 v[116:119], v[16:17], off offset:192
	global_load_dwordx4 v[120:123], v[16:17], off offset:224
	global_load_dwordx4 v[124:127], v[16:17], off offset:256
	global_load_dwordx4 v[128:131], v[16:17], off offset:288
	global_load_dwordx4 v[132:135], v[16:17], off offset:320
	global_load_dwordx4 v[136:139], v[16:17], off offset:352
	global_load_dwordx4 v[140:143], v[16:17], off offset:384
	global_load_dwordx4 v[144:147], v[16:17], off offset:416
	global_load_dwordx4 v[148:151], v[16:17], off offset:448
	global_load_dwordx4 v[152:155], v[16:17], off offset:480
	v_fmac_f32_e32 v47, v64, v64
	v_fmac_f32_e32 v47, v65, v65
	v_fmac_f32_e32 v47, v66, v66
	v_fmac_f32_e32 v47, v67, v67
	v_fmac_f32_e32 v47, v68, v68
	v_fmac_f32_e32 v47, v69, v69
	v_fmac_f32_e32 v47, v70, v70
	v_fmac_f32_e32 v47, v71, v71
	v_fmac_f32_e32 v47, v72, v72
	v_fmac_f32_e32 v47, v73, v73
	v_fmac_f32_e32 v47, v74, v74
	v_fmac_f32_e32 v47, v75, v75
	v_fmac_f32_e32 v47, v76, v76
	v_fmac_f32_e32 v47, v77, v77
	v_fmac_f32_e32 v47, v78, v78
	v_fmac_f32_e32 v47, v79, v79
	v_fmac_f32_e32 v47, v80, v80
	v_fmac_f32_e32 v47, v81, v81
	v_fmac_f32_e32 v47, v82, v82
	v_fmac_f32_e32 v47, v83, v83
	v_fmac_f32_e32 v47, v84, v84
	v_fmac_f32_e32 v47, v85, v85
	v_fmac_f32_e32 v47, v86, v86
	v_fmac_f32_e32 v47, v87, v87
	v_fmac_f32_e32 v47, v88, v88
	v_fmac_f32_e32 v47, v89, v89
	v_fmac_f32_e32 v47, v90, v90
	v_fmac_f32_e32 v47, v91, v91
	s_waitcnt lgkmcnt(8)
; #define LAS __attribute__((address_space(3)))
; __device__ __forceinline__ unsigned cvt_pk_bf16(float lo, float hi) { unsigned r; asm volatile("v_cvt_pk_bf16_f32 %0, %1, %2" : "=v"(r) : "v"(lo), "v"(hi)); return r; }
; __device__ __forceinline__ float xhalf_sum(float v) { auto rr = __builtin_amdgcn_permlane32_swap(__float_as_uint(v), __float_as_uint(v), false, false); return __uint_as_float(rr[0]) + __uint_as_float(rr[1]); }
; __device__ __forceinline__ void attn_phase(const Args& A, LAS unsigned char* lds, int vcu, int G, const int tid) {
;     ...
;             ss = xhalf_sum(ss);
;             const float rn = (1.0f - LAMBDA_INIT) / sqrtf(ss * (1.0f / 128.0f) + RMS_EPS);
;             int ln = lane; asm volatile("" : "+v"(ln));
;             const int er32 = ln & 31, ehi = ln >> 5;
;             LAS unsigned char* stg = lds + 65536 + qi * (32 * 272);
;             const float* sg = A.in[I_SUBG] + 4 * ehi;
; #pragma unroll
;             for (int i = 0; i < 4; ++i)
; #pragma unroll
;                 for (int rq = 0; rq < 4; ++rq) { const f32x4 gq = *(const f32x4*)(sg + 32 * i + 8 * rq);
;                     u32x2 w; w.x = cvt_pk_bf16(o[i][4 * rq] * rn * gq[0], o[i][4 * rq + 1] * rn * gq[1]); w.y = cvt_pk_bf16(o[i][4 * rq + 2] * rn * gq[2], o[i][4 * rq + 3] * rn * gq[3]);
;                     *(LAS u32x2*)(stg + er32 * 272 + (32 * i + 8 * rq + 4 * ehi) * 2) = w; }
	v_fma_f32 v22, v30, v32, -v22
	v_fmac_f32_e32 v47, v22, v22
	v_fma_f32 v23, v31, v32, -v23
	v_fmac_f32_e32 v47, v23, v23
	s_waitcnt lgkmcnt(7)
	v_fma_f32 v24, v0, v32, -v24
	v_fmac_f32_e32 v47, v24, v24
	v_fma_f32 v25, v1, v32, -v25
	v_fmac_f32_e32 v47, v25, v25
	s_waitcnt lgkmcnt(6)
	v_fma_f32 v26, v2, v32, -v26
	v_fmac_f32_e32 v47, v26, v26
	v_fma_f32 v27, v3, v32, -v27
	v_fmac_f32_e32 v47, v27, v27
	s_waitcnt lgkmcnt(5)
	v_fma_f32 v28, v4, v32, -v28
	v_fmac_f32_e32 v47, v28, v28
	v_fma_f32 v29, v5, v32, -v29
	v_fmac_f32_e32 v47, v29, v29
	s_waitcnt lgkmcnt(4)
	v_fma_f32 v6, v6, v32, -v34
	v_fmac_f32_e32 v47, v6, v6
	v_fma_f32 v7, v7, v32, -v35
	v_fmac_f32_e32 v47, v7, v7
	s_waitcnt lgkmcnt(3)
	v_fma_f32 v8, v8, v32, -v36
	v_fmac_f32_e32 v47, v8, v8
	v_fma_f32 v9, v9, v32, -v37
	v_fmac_f32_e32 v47, v9, v9
	s_waitcnt lgkmcnt(2)
	v_fma_f32 v10, v10, v32, -v38
	v_fmac_f32_e32 v47, v10, v10
	v_fma_f32 v11, v11, v32, -v39
	v_fmac_f32_e32 v47, v11, v11
	s_waitcnt lgkmcnt(1)
	v_fma_f32 v30, v12, v32, -v40
	v_fmac_f32_e32 v47, v30, v30
	v_fma_f32 v13, v13, v32, -v41
	v_fmac_f32_e32 v47, v13, v13
	s_waitcnt lgkmcnt(0)
	v_fma_f32 v14, v14, v32, -v42
	v_fmac_f32_e32 v47, v14, v14
	v_fma_f32 v15, v15, v32, -v43
	v_fmac_f32_e32 v47, v15, v15
	v_mov_b32_e32 v0, v47
	s_nop 1
	v_permlane32_swap_b32_e32 v47, v0
	v_add_f32_e32 v0, v47, v0
	v_fmamk_f32 v0, v0, 0x3c000000, v215
	v_mul_f32_e32 v1, 0x4f800000, v0
	v_cmp_gt_f32_e32 vcc, s9, v0
	v_and_b32_e32 v12, 31, v92
	v_mul_u32_u24_e32 v12, 0x110, v12
	v_cndmask_b32_e32 v0, v0, v1, vcc
	v_sqrt_f32_e32 v1, v0
	s_movk_i32 s12, 0x4000
	v_add_u32_e32 v2, -1, v1
	v_fma_f32 v3, -v2, v1, v0
	v_cmp_ge_f32_e64 s[4:5], 0, v3
	v_add_u32_e32 v3, 1, v1
	s_nop 0
	v_cndmask_b32_e64 v2, v1, v2, s[4:5]
	v_fma_f32 v1, -v3, v1, v0
	v_cmp_lt_f32_e64 s[4:5], 0, v1
	s_nop 1
	v_cndmask_b32_e64 v1, v2, v3, s[4:5]
	v_mul_f32_e32 v2, 0x37800000, v1
	v_cndmask_b32_e32 v1, v1, v2, vcc
	v_cmp_class_f32_e32 vcc, v0, v202
	s_movk_i32 s4, 0x110
	s_movk_i32 s5, 0x2000
	v_cndmask_b32_e32 v0, v1, v0, vcc
	v_div_scale_f32 v1, s[2:3], v0, v0, s63
	v_rcp_f32_e32 v2, v1
	s_lshl_b64 s[2:3], s[38:39], 11
	s_add_u32 s13, s18, s2
	s_addc_u32 s14, s19, s3
	v_fma_f32 v3, -v1, v2, 1.0
	v_fmac_f32_e32 v2, v3, v2
	v_div_scale_f32 v3, vcc, s63, v0, s63
	v_mul_f32_e32 v4, v3, v2
	v_fma_f32 v5, -v1, v4, v3
	v_fmac_f32_e32 v4, v5, v2
	v_fma_f32 v1, -v1, v4, v3
	v_div_fmas_f32 v1, v1, v2, v4
	v_div_fixup_f32 v31, v1, v0, s63
	v_mul_f32_e32 v0, v33, v31
	v_mul_f32_e32 v1, v46, v31
	s_waitcnt vmcnt(0)
	v_mul_f32_e32 v0, v18, v0
	v_mul_f32_e32 v1, v19, v1
	v_cvt_pk_bf16_f32 v4, v0, v1
	v_mul_f32_e32 v0, v48, v31
	v_mul_f32_e32 v1, v49, v31
	v_mul_f32_e32 v0, v20, v0
	v_mul_f32_e32 v1, v21, v1
	v_cvt_pk_bf16_f32 v5, v0, v1
	v_lshlrev_b32_e32 v18, 1, v44
	v_add3_u32 v18, s60, v12, v18
	ds_write_b64 v18, v[4:5]
	v_mul_f32_e32 v4, v50, v31
	v_mul_f32_e32 v12, v54, v31
	v_mul_f32_e32 v19, v55, v31
	v_mul_f32_e32 v20, v56, v31
	v_mul_f32_e32 v21, v57, v31
	v_mul_f32_e32 v6, v6, v31
	v_mul_f32_e32 v7, v7, v31
	s_lshl_b64 s[2:3], s[36:37], 1
	s_add_u32 s2, s13, s2
	s_addc_u32 s3, s14, s3
	v_mov_b64_e32 v[0:1], v[96:97]
	v_mov_b64_e32 v[2:3], v[98:99]
	v_mul_f32_e32 v0, v0, v4
	v_mul_f32_e32 v4, v51, v31
	v_mul_f32_e32 v1, v1, v4
	v_cvt_pk_bf16_f32 v4, v0, v1
	v_mul_f32_e32 v0, v52, v31
	v_mul_f32_e32 v1, v53, v31
	v_mul_f32_e32 v0, v2, v0
	v_mul_f32_e32 v1, v3, v1
	v_cvt_pk_bf16_f32 v5, v0, v1
	ds_write_b64 v18, v[4:5] offset:16
	v_mov_b64_e32 v[0:1], v[100:101]
	v_mov_b64_e32 v[2:3], v[102:103]
	v_mul_f32_e32 v0, v12, v0
	v_mul_f32_e32 v1, v19, v1
	v_mul_f32_e32 v2, v20, v2
	v_mul_f32_e32 v3, v21, v3
	v_cvt_pk_bf16_f32 v4, v0, v1
	v_cvt_pk_bf16_f32 v5, v2, v3
	v_mul_f32_e32 v12, v58, v31
	v_mul_f32_e32 v19, v59, v31
	v_mul_f32_e32 v20, v60, v31
	v_mul_f32_e32 v21, v61, v31
	ds_write_b64 v18, v[4:5] offset:32
	v_mov_b64_e32 v[0:1], v[104:105]
	v_mov_b64_e32 v[2:3], v[106:107]
	v_mul_f32_e32 v0, v12, v0
	v_mul_f32_e32 v1, v19, v1
	v_mul_f32_e32 v2, v20, v2
	v_mul_f32_e32 v3, v21, v3
	v_cvt_pk_bf16_f32 v4, v0, v1
	v_cvt_pk_bf16_f32 v5, v2, v3
	v_mul_f32_e32 v12, v62, v31
	v_mul_f32_e32 v19, v63, v31
	v_mul_f32_e32 v20, v64, v31
	v_mul_f32_e32 v21, v65, v31
	ds_write_b64 v18, v[4:5] offset:48
	v_mov_b64_e32 v[0:1], v[108:109]
	v_mov_b64_e32 v[2:3], v[110:111]
	v_mul_f32_e32 v0, v12, v0
	v_mul_f32_e32 v1, v19, v1
	v_mul_f32_e32 v2, v20, v2
	v_mul_f32_e32 v3, v21, v3
	v_cvt_pk_bf16_f32 v4, v0, v1
	v_cvt_pk_bf16_f32 v5, v2, v3
	v_mul_f32_e32 v12, v66, v31
	v_mul_f32_e32 v19, v67, v31
	v_mul_f32_e32 v20, v68, v31
	v_mul_f32_e32 v21, v69, v31
	ds_write_b64 v18, v[4:5] offset:64
	v_mov_b64_e32 v[0:1], v[112:113]
	v_mov_b64_e32 v[2:3], v[114:115]
	v_mul_f32_e32 v0, v12, v0
	v_mul_f32_e32 v1, v19, v1
	v_mul_f32_e32 v2, v20, v2
	v_mul_f32_e32 v3, v21, v3
	v_cvt_pk_bf16_f32 v4, v0, v1
	v_cvt_pk_bf16_f32 v5, v2, v3
	v_mul_f32_e32 v12, v70, v31
	v_mul_f32_e32 v19, v71, v31
	v_mul_f32_e32 v20, v72, v31
	v_mul_f32_e32 v21, v73, v31
	ds_write_b64 v18, v[4:5] offset:80
	v_mov_b64_e32 v[0:1], v[116:117]
	v_mov_b64_e32 v[2:3], v[118:119]
	v_mul_f32_e32 v0, v12, v0
	v_mul_f32_e32 v1, v19, v1
	v_mul_f32_e32 v2, v20, v2
	v_mul_f32_e32 v3, v21, v3
	v_cvt_pk_bf16_f32 v4, v0, v1
	v_cvt_pk_bf16_f32 v5, v2, v3
; #define LAS __attribute__((address_space(3)))
; __device__ __forceinline__ unsigned cvt_pk_bf16(float lo, float hi) { unsigned r; asm volatile("v_cvt_pk_bf16_f32 %0, %1, %2" : "=v"(r) : "v"(lo), "v"(hi)); return r; }
; __device__ __forceinline__ void attn_phase(const Args& A, LAS unsigned char* lds, int vcu, int G, const int tid) {
;     ...
;             for (int i = 0; i < 4; ++i)
; #pragma unroll
;                 for (int rq = 0; rq < 4; ++rq) { const f32x4 gq = *(const f32x4*)(sg + 32 * i + 8 * rq);
;                     u32x2 w; w.x = cvt_pk_bf16(o[i][4 * rq] * rn * gq[0], o[i][4 * rq + 1] * rn * gq[1]); w.y = cvt_pk_bf16(o[i][4 * rq + 2] * rn * gq[2], o[i][4 * rq + 3] * rn * gq[3]);
;                     *(LAS u32x2*)(stg + er32 * 272 + (32 * i + 8 * rq + 4 * ehi) * 2) = w; }
;             asm volatile("s_waitcnt lgkmcnt(0)" ::: "memory");
;             bf16_t* obase = AO + (size_t)(qrow - r32) * DM + h * 128;
; #pragma unroll
;             for (int k = 0; k < 8; ++k) { const int row = 4 * k + (ln >> 4), ch = ln & 15;
;                 const u32x4 v = *(const LAS u32x4*)(stg + row * 272 + ch * 16);
;                 *(u32x4*)(obase + (size_t)row * DM + ch * 8) = v;
;                 if (k & 1) asm volatile("" ::: "memory"); }
	v_mul_f32_e32 v12, v74, v31
	v_mul_f32_e32 v19, v75, v31
	v_mul_f32_e32 v20, v76, v31
	v_mul_f32_e32 v21, v77, v31
	ds_write_b64 v18, v[4:5] offset:96
	v_mov_b64_e32 v[0:1], v[120:121]
	v_mov_b64_e32 v[2:3], v[122:123]
	v_mul_f32_e32 v0, v12, v0
	v_mul_f32_e32 v1, v19, v1
	v_mul_f32_e32 v2, v20, v2
	v_mul_f32_e32 v3, v21, v3
	v_cvt_pk_bf16_f32 v4, v0, v1
	v_cvt_pk_bf16_f32 v5, v2, v3
	v_mul_f32_e32 v12, v78, v31
	v_mul_f32_e32 v19, v79, v31
	v_mul_f32_e32 v20, v80, v31
	v_mul_f32_e32 v21, v81, v31
	ds_write_b64 v18, v[4:5] offset:112
	v_mov_b64_e32 v[0:1], v[124:125]
	v_mov_b64_e32 v[2:3], v[126:127]
	v_mul_f32_e32 v0, v12, v0
	v_mul_f32_e32 v1, v19, v1
	v_mul_f32_e32 v2, v20, v2
	v_mul_f32_e32 v3, v21, v3
	v_cvt_pk_bf16_f32 v4, v0, v1
	v_cvt_pk_bf16_f32 v5, v2, v3
	v_mul_f32_e32 v12, v82, v31
	v_mul_f32_e32 v19, v83, v31
	v_mul_f32_e32 v20, v84, v31
	v_mul_f32_e32 v21, v85, v31
	ds_write_b64 v18, v[4:5] offset:128
	v_mov_b64_e32 v[0:1], v[128:129]
	v_mov_b64_e32 v[2:3], v[130:131]
	v_mul_f32_e32 v0, v12, v0
	v_mul_f32_e32 v1, v19, v1
	v_mul_f32_e32 v2, v20, v2
	v_mul_f32_e32 v3, v21, v3
	v_cvt_pk_bf16_f32 v4, v0, v1
	v_cvt_pk_bf16_f32 v5, v2, v3
	v_mul_f32_e32 v12, v86, v31
	v_mul_f32_e32 v19, v87, v31
	v_mul_f32_e32 v20, v88, v31
	v_mul_f32_e32 v21, v89, v31
	ds_write_b64 v18, v[4:5] offset:144
	v_mov_b64_e32 v[0:1], v[132:133]
	v_mov_b64_e32 v[2:3], v[134:135]
	v_mul_f32_e32 v0, v12, v0
	v_mul_f32_e32 v1, v19, v1
	v_mul_f32_e32 v2, v20, v2
	v_mul_f32_e32 v3, v21, v3
	v_cvt_pk_bf16_f32 v4, v0, v1
	v_cvt_pk_bf16_f32 v5, v2, v3
	v_mul_f32_e32 v12, v90, v31
	v_mul_f32_e32 v19, v91, v31
	v_mul_f32_e32 v20, v22, v31
	v_mul_f32_e32 v21, v23, v31
	ds_write_b64 v18, v[4:5] offset:160
	v_mov_b64_e32 v[0:1], v[136:137]
	v_mov_b64_e32 v[2:3], v[138:139]
	v_mul_f32_e32 v0, v12, v0
	v_mul_f32_e32 v1, v19, v1
	v_mul_f32_e32 v2, v20, v2
	v_mul_f32_e32 v3, v21, v3
	v_cvt_pk_bf16_f32 v4, v0, v1
	v_cvt_pk_bf16_f32 v5, v2, v3
	v_mul_f32_e32 v12, v24, v31
	v_mul_f32_e32 v19, v25, v31
	v_mul_f32_e32 v20, v26, v31
	v_mul_f32_e32 v21, v27, v31
	ds_write_b64 v18, v[4:5] offset:176
	v_mov_b64_e32 v[0:1], v[140:141]
	v_mov_b64_e32 v[2:3], v[142:143]
	v_mul_f32_e32 v0, v12, v0
	v_mul_f32_e32 v1, v19, v1
	v_mul_f32_e32 v2, v20, v2
	v_mul_f32_e32 v3, v21, v3
	v_cvt_pk_bf16_f32 v4, v0, v1
	v_cvt_pk_bf16_f32 v5, v2, v3
	v_mul_f32_e32 v12, v28, v31
	v_mul_f32_e32 v19, v29, v31
	ds_write_b64 v18, v[4:5] offset:192
	v_mov_b64_e32 v[0:1], v[144:145]
	v_mov_b64_e32 v[2:3], v[146:147]
	v_mul_f32_e32 v0, v12, v0
	v_mul_f32_e32 v1, v19, v1
	v_mul_f32_e32 v2, v6, v2
	v_mul_f32_e32 v3, v7, v3
	v_cvt_pk_bf16_f32 v4, v0, v1
	v_cvt_pk_bf16_f32 v5, v2, v3
	v_mul_f32_e32 v6, v8, v31
	v_mul_f32_e32 v7, v9, v31
	v_mul_f32_e32 v8, v10, v31
	v_mul_f32_e32 v9, v11, v31
	ds_write_b64 v18, v[4:5] offset:208
	v_mul_f32_e32 v19, v15, v31
	v_mov_b64_e32 v[0:1], v[148:149]
	v_mov_b64_e32 v[2:3], v[150:151]
	v_mul_f32_e32 v0, v6, v0
	v_mul_f32_e32 v1, v7, v1
	v_mul_f32_e32 v2, v8, v2
	v_mul_f32_e32 v3, v9, v3
	v_cvt_pk_bf16_f32 v4, v0, v1
	v_cvt_pk_bf16_f32 v5, v2, v3
	v_ashrrev_i32_e32 v8, 4, v92
	v_lshlrev_b32_e32 v6, 4, v92
	v_mov_b32_e32 v7, v191
	v_and_b32_e32 v6, 0xf0, v6
	v_mul_lo_u32 v10, v8, s4
	v_ashrrev_i32_e32 v9, 31, v8
	v_add3_u32 v20, s60, v6, v10
	v_lshlrev_b64 v[8:9], 11, v[8:9]
	v_lshl_add_u64 v[6:7], s[2:3], 0, v[6:7]
	v_lshl_add_u64 v[8:9], v[6:7], 0, v[8:9]
	v_mul_f32_e32 v6, v30, v31
	v_mul_f32_e32 v7, v13, v31
	v_mul_f32_e32 v17, v14, v31
	ds_write_b64 v18, v[4:5] offset:224
	v_add_co_u32_e32 v10, vcc, s5, v8
	v_mov_b64_e32 v[0:1], v[152:153]
	v_mov_b64_e32 v[2:3], v[154:155]
	v_mul_f32_e32 v0, v6, v0
	v_mul_f32_e32 v1, v7, v1
	v_mul_f32_e32 v2, v17, v2
	v_mul_f32_e32 v3, v19, v3
	v_cvt_pk_bf16_f32 v0, v0, v1
	v_cvt_pk_bf16_f32 v1, v2, v3
	ds_write_b64 v18, v[0:1] offset:240
	s_waitcnt lgkmcnt(0)
	ds_read_b128 v[0:3], v20
	ds_read_b128 v[4:7], v20 offset:1088
	v_addc_co_u32_e32 v11, vcc, 0, v9, vcc
	s_waitcnt lgkmcnt(1)
	global_store_dwordx4 v[8:9], v[0:3], off
	s_waitcnt lgkmcnt(0)
	global_store_dwordx4 v[10:11], v[4:7], off
	ds_read_b128 v[0:3], v20 offset:2176
	ds_read_b128 v[4:7], v20 offset:3264
	v_add_co_u32_e32 v12, vcc, s12, v8
	s_nop 1
	v_addc_co_u32_e32 v13, vcc, 0, v9, vcc
	v_add_co_u32_e32 v14, vcc, 0x6000, v8
	s_nop 1
	v_addc_co_u32_e32 v15, vcc, 0, v9, vcc
	s_waitcnt lgkmcnt(1)
	global_store_dwordx4 v[12:13], v[0:3], off
	s_waitcnt lgkmcnt(0)
	global_store_dwordx4 v[14:15], v[4:7], off
	ds_read_b128 v[0:3], v20 offset:4352
	ds_read_b128 v[4:7], v20 offset:5440
	v_add_co_u32_e32 v16, vcc, 0x8000, v8
	s_nop 1
	v_addc_co_u32_e32 v17, vcc, 0, v9, vcc
	v_add_co_u32_e32 v18, vcc, 0xa000, v8
	s_nop 1
	v_addc_co_u32_e32 v19, vcc, 0, v9, vcc
	s_waitcnt lgkmcnt(1)
	global_store_dwordx4 v[16:17], v[0:3], off
	s_waitcnt lgkmcnt(0)
	global_store_dwordx4 v[18:19], v[4:7], off
	ds_read_b128 v[0:3], v20 offset:6528
	ds_read_b128 v[4:7], v20 offset:7616
	v_add_co_u32_e32 v10, vcc, 0xc000, v8
	s_nop 1
	v_addc_co_u32_e32 v11, vcc, 0, v9, vcc
	v_add_co_u32_e32 v8, vcc, 0xe000, v8
	s_nop 1
	v_addc_co_u32_e32 v9, vcc, 0, v9, vcc
	s_waitcnt lgkmcnt(1)
	global_store_dwordx4 v[10:11], v[0:3], off
	s_waitcnt lgkmcnt(0)
	global_store_dwordx4 v[8:9], v[4:7], off
	s_branch .LBB0_839
